# GEMM tiles: first K-steps peeled with C=0 instead of 64 accumulator-zeroing moves per tile
# baseline (speedup 1.0000x reference)
.LBB0_241:
	s_mov_b64 s[8:9], 0x80
	v_lshl_add_u64 v[114:115], v[114:115], 0, s[8:9]
	v_mov_b32_e32 v38, 0
	s_mov_b32 s3, s2
	v_lshl_add_u64 v[116:117], v[114:115], 0, v[100:101]
	v_lshl_add_u64 v[118:119], v[114:115], 0, v[102:103]
	v_lshl_add_u64 v[120:121], v[114:115], 0, v[104:105]
	s_mov_b64 s[4:5], 0
	s_mov_b32 s2, 0
	v_readfirstlane_b32 s60, v98
	v_readfirstlane_b32 s61, v99
	v_readfirstlane_b32 s62, v114
	v_readfirstlane_b32 s63, v115
	v_readfirstlane_b32 s64, v122
	v_subrev_u32_e32 v140, s60, v98
	v_subrev_u32_e32 v144, s62, v114
	v_subrev_u32_e32 v145, s62, v116
	v_subrev_u32_e32 v146, s62, v118
	v_subrev_u32_e32 v147, s62, v120
	v_add_u32_e32 v141, 0x10000, v140
	v_add_u32_e32 v142, 0x20000, v140
	v_add_u32_e32 v143, 0x30000, v140
	v_add3_u32 v136, v131, v132, v133
	v_add3_u32 v137, v131, v134, v133
	v_add3_u32 v138, v130, v132, v133
	v_add3_u32 v139, v130, v134, v133
	s_add_u32 s60, s60, 0x80
	s_addc_u32 s61, s61, 0
	s_add_u32 m0, s64, 0x8000
	s_nop 0
	global_load_lds_dwordx4 v140, s[60:61]
	s_add_u32 m0, s64, 0x9000
	s_nop 0
	global_load_lds_dwordx4 v141, s[60:61]
	s_add_u32 m0, s64, 0xa000
	s_nop 0
	global_load_lds_dwordx4 v142, s[60:61]
	s_add_u32 m0, s64, 0xb000
	s_nop 0
	global_load_lds_dwordx4 v143, s[60:61]
	s_add_u32 s60, s60, 0x80
	s_addc_u32 s61, s61, 0
	s_mov_b64 s[10:11], 0x10080
	s_mov_b64 s[12:13], 0x20080
	s_mov_b64 s[14:15], 0x30080
	s_waitcnt vmcnt(4) lgkmcnt(0)
	s_barrier
	ds_read_b128 v[66:69], v136 offset:0
	ds_read_b128 v[82:85], v137 offset:16384
	ds_read_b128 v[86:89], v137 offset:18432
	ds_read_b128 v[70:73], v136 offset:2048
	ds_read_b128 v[90:93], v137 offset:20480
	ds_read_b128 v[94:97], v137 offset:22528
	ds_read_b128 v[74:77], v136 offset:4096
	ds_read_b128 v[78:81], v136 offset:6144
	ds_read_b128 v[148:151], v138 offset:0
	ds_read_b128 v[172:175], v139 offset:16384
	ds_read_b128 v[176:179], v139 offset:18432
	ds_read_b128 v[152:155], v138 offset:2048
	ds_read_b128 v[180:183], v139 offset:20480
	ds_read_b128 v[184:187], v139 offset:22528
	ds_read_b128 v[156:159], v138 offset:4096
	ds_read_b128 v[168:171], v138 offset:6144
	s_waitcnt lgkmcnt(8)
	s_add_u32 m0, s64, 0xc000
	v_mfma_f32_16x16x32_bf16 v[62:65], v[66:69], v[82:85], 0
	v_mfma_f32_16x16x32_bf16 v[58:61], v[66:69], v[86:89], 0
	global_load_lds_dwordx4 v144, s[62:63]
	v_mfma_f32_16x16x32_bf16 v[54:57], v[66:69], v[90:93], 0
	v_mfma_f32_16x16x32_bf16 v[50:53], v[66:69], v[94:97], 0
	s_add_u32 m0, s64, 0xd000
	v_mfma_f32_16x16x32_bf16 v[46:49], v[70:73], v[82:85], 0
	v_mfma_f32_16x16x32_bf16 v[42:45], v[70:73], v[86:89], 0
	global_load_lds_dwordx4 v145, s[62:63]
	v_mfma_f32_16x16x32_bf16 v[34:37], v[70:73], v[90:93], 0
	v_mfma_f32_16x16x32_bf16 v[30:33], v[70:73], v[94:97], 0
	s_add_u32 m0, s64, 0xe000
	v_mfma_f32_16x16x32_bf16 v[26:29], v[74:77], v[82:85], 0
	v_mfma_f32_16x16x32_bf16 v[22:25], v[74:77], v[86:89], 0
	global_load_lds_dwordx4 v146, s[62:63]
	v_mfma_f32_16x16x32_bf16 v[18:21], v[74:77], v[90:93], 0
	v_mfma_f32_16x16x32_bf16 v[14:17], v[74:77], v[94:97], 0
	s_add_u32 m0, s64, 0xf000
	v_mfma_f32_16x16x32_bf16 v[10:13], v[78:81], v[82:85], 0
	v_mfma_f32_16x16x32_bf16 v[6:9], v[78:81], v[86:89], 0
	global_load_lds_dwordx4 v147, s[62:63]
	v_mfma_f32_16x16x32_bf16 v[2:5], v[78:81], v[90:93], 0
	v_mfma_f32_16x16x32_bf16 v[38:41], v[78:81], v[94:97], 0
	s_add_u32 s62, s62, 0x80
	s_addc_u32 s63, s63, 0
	s_waitcnt lgkmcnt(0)
	s_barrier
	s_add_u32 m0, s64, 0x0
	v_mfma_f32_16x16x32_bf16 v[62:65], v[148:151], v[172:175], v[62:65]
	v_mfma_f32_16x16x32_bf16 v[58:61], v[148:151], v[176:179], v[58:61]
	global_load_lds_dwordx4 v140, s[60:61]
	v_mfma_f32_16x16x32_bf16 v[54:57], v[148:151], v[180:183], v[54:57]
	v_mfma_f32_16x16x32_bf16 v[50:53], v[148:151], v[184:187], v[50:53]
	s_add_u32 m0, s64, 0x1000
	v_mfma_f32_16x16x32_bf16 v[46:49], v[152:155], v[172:175], v[46:49]
	v_mfma_f32_16x16x32_bf16 v[42:45], v[152:155], v[176:179], v[42:45]
	global_load_lds_dwordx4 v141, s[60:61]
	v_mfma_f32_16x16x32_bf16 v[34:37], v[152:155], v[180:183], v[34:37]
	v_mfma_f32_16x16x32_bf16 v[30:33], v[152:155], v[184:187], v[30:33]
	s_waitcnt vmcnt(2)
	s_barrier
	ds_read_b128 v[66:69], v136 offset:32768
	ds_read_b128 v[82:85], v137 offset:49152
	ds_read_b128 v[86:89], v137 offset:51200
	ds_read_b128 v[70:73], v136 offset:34816
	ds_read_b128 v[90:93], v137 offset:53248
	ds_read_b128 v[94:97], v137 offset:55296
	ds_read_b128 v[74:77], v136 offset:36864
	ds_read_b128 v[78:81], v136 offset:38912
	s_add_u32 m0, s64, 0x2000
	v_mfma_f32_16x16x32_bf16 v[26:29], v[156:159], v[172:175], v[26:29]
	v_mfma_f32_16x16x32_bf16 v[22:25], v[156:159], v[176:179], v[22:25]
	global_load_lds_dwordx4 v142, s[60:61]
	v_mfma_f32_16x16x32_bf16 v[18:21], v[156:159], v[180:183], v[18:21]
	v_mfma_f32_16x16x32_bf16 v[14:17], v[156:159], v[184:187], v[14:17]
	s_add_u32 m0, s64, 0x3000
	v_mfma_f32_16x16x32_bf16 v[10:13], v[168:171], v[172:175], v[10:13]
	v_mfma_f32_16x16x32_bf16 v[6:9], v[168:171], v[176:179], v[6:9]
	global_load_lds_dwordx4 v143, s[60:61]
	v_mfma_f32_16x16x32_bf16 v[2:5], v[168:171], v[180:183], v[2:5]
	v_mfma_f32_16x16x32_bf16 v[38:41], v[168:171], v[184:187], v[38:41]
	s_add_u32 s60, s60, 0x80
	s_addc_u32 s61, s61, 0
	ds_read_b128 v[148:151], v138 offset:32768
	ds_read_b128 v[172:175], v139 offset:49152
	ds_read_b128 v[176:179], v139 offset:51200
	ds_read_b128 v[152:155], v138 offset:34816
	ds_read_b128 v[180:183], v139 offset:53248
	ds_read_b128 v[184:187], v139 offset:55296
	ds_read_b128 v[156:159], v138 offset:36864
	ds_read_b128 v[168:171], v138 offset:38912
	s_waitcnt lgkmcnt(8)
	s_add_u32 m0, s64, 0x4000
	v_mfma_f32_16x16x32_bf16 v[62:65], v[66:69], v[82:85], v[62:65]
	v_mfma_f32_16x16x32_bf16 v[58:61], v[66:69], v[86:89], v[58:61]
	global_load_lds_dwordx4 v144, s[62:63]
	v_mfma_f32_16x16x32_bf16 v[54:57], v[66:69], v[90:93], v[54:57]
	v_mfma_f32_16x16x32_bf16 v[50:53], v[66:69], v[94:97], v[50:53]
	s_add_u32 m0, s64, 0x5000
	v_mfma_f32_16x16x32_bf16 v[46:49], v[70:73], v[82:85], v[46:49]
	v_mfma_f32_16x16x32_bf16 v[42:45], v[70:73], v[86:89], v[42:45]
	global_load_lds_dwordx4 v145, s[62:63]
	v_mfma_f32_16x16x32_bf16 v[34:37], v[70:73], v[90:93], v[34:37]
	v_mfma_f32_16x16x32_bf16 v[30:33], v[70:73], v[94:97], v[30:33]
	s_add_u32 m0, s64, 0x6000
	v_mfma_f32_16x16x32_bf16 v[26:29], v[74:77], v[82:85], v[26:29]
	v_mfma_f32_16x16x32_bf16 v[22:25], v[74:77], v[86:89], v[22:25]
	global_load_lds_dwordx4 v146, s[62:63]
	v_mfma_f32_16x16x32_bf16 v[18:21], v[74:77], v[90:93], v[18:21]
	v_mfma_f32_16x16x32_bf16 v[14:17], v[74:77], v[94:97], v[14:17]
	s_add_u32 m0, s64, 0x7000
	v_mfma_f32_16x16x32_bf16 v[10:13], v[78:81], v[82:85], v[10:13]
	v_mfma_f32_16x16x32_bf16 v[6:9], v[78:81], v[86:89], v[6:9]
	global_load_lds_dwordx4 v147, s[62:63]
	v_mfma_f32_16x16x32_bf16 v[2:5], v[78:81], v[90:93], v[2:5]
	v_mfma_f32_16x16x32_bf16 v[38:41], v[78:81], v[94:97], v[38:41]
	s_add_u32 s62, s62, 0x80
	s_addc_u32 s63, s63, 0
	s_waitcnt lgkmcnt(0)
	s_barrier
	s_add_u32 m0, s64, 0x8000
	v_mfma_f32_16x16x32_bf16 v[62:65], v[148:151], v[172:175], v[62:65]
	v_mfma_f32_16x16x32_bf16 v[58:61], v[148:151], v[176:179], v[58:61]
	global_load_lds_dwordx4 v140, s[60:61]
	v_mfma_f32_16x16x32_bf16 v[54:57], v[148:151], v[180:183], v[54:57]
	v_mfma_f32_16x16x32_bf16 v[50:53], v[148:151], v[184:187], v[50:53]
	s_add_u32 m0, s64, 0x9000
	v_mfma_f32_16x16x32_bf16 v[46:49], v[152:155], v[172:175], v[46:49]
	v_mfma_f32_16x16x32_bf16 v[42:45], v[152:155], v[176:179], v[42:45]
	global_load_lds_dwordx4 v141, s[60:61]
	v_mfma_f32_16x16x32_bf16 v[34:37], v[152:155], v[180:183], v[34:37]
	v_mfma_f32_16x16x32_bf16 v[30:33], v[152:155], v[184:187], v[30:33]
	s_waitcnt vmcnt(2)
	s_barrier
	ds_read_b128 v[66:69], v136 offset:0
	ds_read_b128 v[82:85], v137 offset:16384
	ds_read_b128 v[86:89], v137 offset:18432
	ds_read_b128 v[70:73], v136 offset:2048
	ds_read_b128 v[90:93], v137 offset:20480
	ds_read_b128 v[94:97], v137 offset:22528
	ds_read_b128 v[74:77], v136 offset:4096
	ds_read_b128 v[78:81], v136 offset:6144
	s_add_u32 m0, s64, 0xa000
	v_mfma_f32_16x16x32_bf16 v[26:29], v[156:159], v[172:175], v[26:29]
	v_mfma_f32_16x16x32_bf16 v[22:25], v[156:159], v[176:179], v[22:25]
	global_load_lds_dwordx4 v142, s[60:61]
	v_mfma_f32_16x16x32_bf16 v[18:21], v[156:159], v[180:183], v[18:21]
	v_mfma_f32_16x16x32_bf16 v[14:17], v[156:159], v[184:187], v[14:17]
	s_add_u32 m0, s64, 0xb000
	v_mfma_f32_16x16x32_bf16 v[10:13], v[168:171], v[172:175], v[10:13]
	v_mfma_f32_16x16x32_bf16 v[6:9], v[168:171], v[176:179], v[6:9]
	global_load_lds_dwordx4 v143, s[60:61]
	v_mfma_f32_16x16x32_bf16 v[2:5], v[168:171], v[180:183], v[2:5]
	v_mfma_f32_16x16x32_bf16 v[38:41], v[168:171], v[184:187], v[38:41]
	s_add_u32 s60, s60, 0x80
	s_addc_u32 s61, s61, 0
	s_mov_b32 s65, 6

.LBB0_508:
	v_cmp_gt_i32_e32 vcc, s2, v117
	s_mov_b64 s[0:1], 0x80
	v_lshl_add_u64 v[104:105], v[66:67], 0, s[0:1]
	v_cndmask_b32_e32 v0, 0, v199, vcc
	v_cmp_gt_i32_e32 vcc, s2, v119
	v_mov_b32_e32 v3, v1
	v_mov_b32_e32 v5, v1
	v_cndmask_b32_e32 v2, 0, v206, vcc
	v_cmp_gt_i32_e32 vcc, s2, v121
	v_mov_b32_e32 v42, 0
	s_mov_b32 s4, 0
	v_cndmask_b32_e32 v4, 0, v207, vcc
	v_lshl_add_u64 v[106:107], v[104:105], 0, v[0:1]
	v_lshl_add_u64 v[108:109], v[104:105], 0, v[2:3]
	v_lshl_add_u64 v[110:111], v[104:105], 0, v[4:5]
	s_mov_b64 s[0:1], 0
	v_readfirstlane_b32 s60, v98
	v_readfirstlane_b32 s61, v99
	v_readfirstlane_b32 s62, v104
	v_readfirstlane_b32 s63, v105
	v_readfirstlane_b32 s64, v112
	v_subrev_u32_e32 v140, s60, v98
	v_subrev_u32_e32 v144, s62, v104
	v_subrev_u32_e32 v145, s62, v106
	v_subrev_u32_e32 v146, s62, v108
	v_subrev_u32_e32 v147, s62, v110
	v_add_u32_e32 v141, 0x10000, v140
	v_add_u32_e32 v142, 0x20000, v140
	v_add_u32_e32 v143, 0x30000, v140
	v_add3_u32 v136, v124, v125, v126
	v_add3_u32 v137, v124, v127, v126
	v_add3_u32 v138, v123, v125, v126
	v_add3_u32 v139, v123, v127, v126
	s_add_u32 s60, s60, 0x80
	s_addc_u32 s61, s61, 0
	s_add_u32 m0, s64, 0x8000
	s_nop 0
	global_load_lds_dwordx4 v140, s[60:61]
	s_add_u32 m0, s64, 0x9000
	s_nop 0
	global_load_lds_dwordx4 v141, s[60:61]
	s_add_u32 m0, s64, 0xa000
	s_nop 0
	global_load_lds_dwordx4 v142, s[60:61]
	s_add_u32 m0, s64, 0xb000
	s_nop 0
	global_load_lds_dwordx4 v143, s[60:61]
	s_add_u32 s60, s60, 0x80
	s_addc_u32 s61, s61, 0
	s_mov_b64 s[12:13], 0x10000
	s_mov_b64 s[14:15], 0x20000
	s_mov_b64 s[16:17], 0x30000
	s_mov_b64 s[8:9], 0x10080
	s_mov_b64 s[10:11], 0x20080
	s_mov_b64 s[18:19], 0x30080
	s_waitcnt vmcnt(4) lgkmcnt(0)
	s_barrier
	ds_read_b128 v[66:69], v136 offset:0
	ds_read_b128 v[82:85], v137 offset:16384
	ds_read_b128 v[86:89], v137 offset:18432
	ds_read_b128 v[70:73], v136 offset:2048
	ds_read_b128 v[90:93], v137 offset:20480
	ds_read_b128 v[94:97], v137 offset:22528
	ds_read_b128 v[74:77], v136 offset:4096
	ds_read_b128 v[78:81], v136 offset:6144
	ds_read_b128 v[148:151], v138 offset:0
	ds_read_b128 v[172:175], v139 offset:16384
	ds_read_b128 v[176:179], v139 offset:18432
	ds_read_b128 v[152:155], v138 offset:2048
	ds_read_b128 v[180:183], v139 offset:20480
	ds_read_b128 v[184:187], v139 offset:22528
	ds_read_b128 v[156:159], v138 offset:4096
	ds_read_b128 v[168:171], v138 offset:6144
	s_waitcnt lgkmcnt(8)
	s_add_u32 m0, s64, 0xc000
	v_mfma_f32_16x16x32_bf16 v[62:65], v[66:69], v[82:85], 0
	v_mfma_f32_16x16x32_bf16 v[58:61], v[66:69], v[86:89], 0
	global_load_lds_dwordx4 v144, s[62:63]
	v_mfma_f32_16x16x32_bf16 v[54:57], v[66:69], v[90:93], 0
	v_mfma_f32_16x16x32_bf16 v[50:53], v[66:69], v[94:97], 0
	s_add_u32 m0, s64, 0xd000
	v_mfma_f32_16x16x32_bf16 v[46:49], v[70:73], v[82:85], 0
	v_mfma_f32_16x16x32_bf16 v[38:41], v[70:73], v[86:89], 0
	global_load_lds_dwordx4 v145, s[62:63]
	v_mfma_f32_16x16x32_bf16 v[34:37], v[70:73], v[90:93], 0
	v_mfma_f32_16x16x32_bf16 v[30:33], v[70:73], v[94:97], 0
	s_add_u32 m0, s64, 0xe000
	v_mfma_f32_16x16x32_bf16 v[26:29], v[74:77], v[82:85], 0
	v_mfma_f32_16x16x32_bf16 v[22:25], v[74:77], v[86:89], 0
	global_load_lds_dwordx4 v146, s[62:63]
	v_mfma_f32_16x16x32_bf16 v[18:21], v[74:77], v[90:93], 0
	v_mfma_f32_16x16x32_bf16 v[14:17], v[74:77], v[94:97], 0
	s_add_u32 m0, s64, 0xf000
	v_mfma_f32_16x16x32_bf16 v[10:13], v[78:81], v[82:85], 0
	v_mfma_f32_16x16x32_bf16 v[6:9], v[78:81], v[86:89], 0
	global_load_lds_dwordx4 v147, s[62:63]
	v_mfma_f32_16x16x32_bf16 v[2:5], v[78:81], v[90:93], 0
	v_mfma_f32_16x16x32_bf16 v[42:45], v[78:81], v[94:97], 0
	s_add_u32 s62, s62, 0x80
	s_addc_u32 s63, s63, 0
	s_waitcnt lgkmcnt(0)
	s_barrier
	s_add_u32 m0, s64, 0x0
	v_mfma_f32_16x16x32_bf16 v[62:65], v[148:151], v[172:175], v[62:65]
	v_mfma_f32_16x16x32_bf16 v[58:61], v[148:151], v[176:179], v[58:61]
	global_load_lds_dwordx4 v140, s[60:61]
	v_mfma_f32_16x16x32_bf16 v[54:57], v[148:151], v[180:183], v[54:57]
	v_mfma_f32_16x16x32_bf16 v[50:53], v[148:151], v[184:187], v[50:53]
	s_add_u32 m0, s64, 0x1000
	v_mfma_f32_16x16x32_bf16 v[46:49], v[152:155], v[172:175], v[46:49]
	v_mfma_f32_16x16x32_bf16 v[38:41], v[152:155], v[176:179], v[38:41]
	global_load_lds_dwordx4 v141, s[60:61]
	v_mfma_f32_16x16x32_bf16 v[34:37], v[152:155], v[180:183], v[34:37]
	v_mfma_f32_16x16x32_bf16 v[30:33], v[152:155], v[184:187], v[30:33]
	s_waitcnt vmcnt(2)
	s_barrier
	ds_read_b128 v[66:69], v136 offset:32768
	ds_read_b128 v[82:85], v137 offset:49152
	ds_read_b128 v[86:89], v137 offset:51200
	ds_read_b128 v[70:73], v136 offset:34816
	ds_read_b128 v[90:93], v137 offset:53248
	ds_read_b128 v[94:97], v137 offset:55296
	ds_read_b128 v[74:77], v136 offset:36864
	ds_read_b128 v[78:81], v136 offset:38912
	s_add_u32 m0, s64, 0x2000
	v_mfma_f32_16x16x32_bf16 v[26:29], v[156:159], v[172:175], v[26:29]
	v_mfma_f32_16x16x32_bf16 v[22:25], v[156:159], v[176:179], v[22:25]
	global_load_lds_dwordx4 v142, s[60:61]
	v_mfma_f32_16x16x32_bf16 v[18:21], v[156:159], v[180:183], v[18:21]
	v_mfma_f32_16x16x32_bf16 v[14:17], v[156:159], v[184:187], v[14:17]
	s_add_u32 m0, s64, 0x3000
	v_mfma_f32_16x16x32_bf16 v[10:13], v[168:171], v[172:175], v[10:13]
	v_mfma_f32_16x16x32_bf16 v[6:9], v[168:171], v[176:179], v[6:9]
	global_load_lds_dwordx4 v143, s[60:61]
	v_mfma_f32_16x16x32_bf16 v[2:5], v[168:171], v[180:183], v[2:5]
	v_mfma_f32_16x16x32_bf16 v[42:45], v[168:171], v[184:187], v[42:45]
	s_add_u32 s60, s60, 0x80
	s_addc_u32 s61, s61, 0
	ds_read_b128 v[148:151], v138 offset:32768
	ds_read_b128 v[172:175], v139 offset:49152
	ds_read_b128 v[176:179], v139 offset:51200
	ds_read_b128 v[152:155], v138 offset:34816
	ds_read_b128 v[180:183], v139 offset:53248
	ds_read_b128 v[184:187], v139 offset:55296
	ds_read_b128 v[156:159], v138 offset:36864
	ds_read_b128 v[168:171], v138 offset:38912
	s_waitcnt lgkmcnt(8)
	s_add_u32 m0, s64, 0x4000
	v_mfma_f32_16x16x32_bf16 v[62:65], v[66:69], v[82:85], v[62:65]
	v_mfma_f32_16x16x32_bf16 v[58:61], v[66:69], v[86:89], v[58:61]
	global_load_lds_dwordx4 v144, s[62:63]
	v_mfma_f32_16x16x32_bf16 v[54:57], v[66:69], v[90:93], v[54:57]
	v_mfma_f32_16x16x32_bf16 v[50:53], v[66:69], v[94:97], v[50:53]
	s_add_u32 m0, s64, 0x5000
	v_mfma_f32_16x16x32_bf16 v[46:49], v[70:73], v[82:85], v[46:49]
	v_mfma_f32_16x16x32_bf16 v[38:41], v[70:73], v[86:89], v[38:41]
	global_load_lds_dwordx4 v145, s[62:63]
	v_mfma_f32_16x16x32_bf16 v[34:37], v[70:73], v[90:93], v[34:37]
	v_mfma_f32_16x16x32_bf16 v[30:33], v[70:73], v[94:97], v[30:33]
	s_add_u32 m0, s64, 0x6000
	v_mfma_f32_16x16x32_bf16 v[26:29], v[74:77], v[82:85], v[26:29]
	v_mfma_f32_16x16x32_bf16 v[22:25], v[74:77], v[86:89], v[22:25]
	global_load_lds_dwordx4 v146, s[62:63]
	v_mfma_f32_16x16x32_bf16 v[18:21], v[74:77], v[90:93], v[18:21]
	v_mfma_f32_16x16x32_bf16 v[14:17], v[74:77], v[94:97], v[14:17]
	s_add_u32 m0, s64, 0x7000
	v_mfma_f32_16x16x32_bf16 v[10:13], v[78:81], v[82:85], v[10:13]
	v_mfma_f32_16x16x32_bf16 v[6:9], v[78:81], v[86:89], v[6:9]
	global_load_lds_dwordx4 v147, s[62:63]
	v_mfma_f32_16x16x32_bf16 v[2:5], v[78:81], v[90:93], v[2:5]
	v_mfma_f32_16x16x32_bf16 v[42:45], v[78:81], v[94:97], v[42:45]
	s_add_u32 s62, s62, 0x80
	s_addc_u32 s63, s63, 0
	s_waitcnt lgkmcnt(0)
	s_barrier
	s_add_u32 m0, s64, 0x8000
	v_mfma_f32_16x16x32_bf16 v[62:65], v[148:151], v[172:175], v[62:65]
	v_mfma_f32_16x16x32_bf16 v[58:61], v[148:151], v[176:179], v[58:61]
	global_load_lds_dwordx4 v140, s[60:61]
	v_mfma_f32_16x16x32_bf16 v[54:57], v[148:151], v[180:183], v[54:57]
	v_mfma_f32_16x16x32_bf16 v[50:53], v[148:151], v[184:187], v[50:53]
	s_add_u32 m0, s64, 0x9000
	v_mfma_f32_16x16x32_bf16 v[46:49], v[152:155], v[172:175], v[46:49]
	v_mfma_f32_16x16x32_bf16 v[38:41], v[152:155], v[176:179], v[38:41]
	global_load_lds_dwordx4 v141, s[60:61]
	v_mfma_f32_16x16x32_bf16 v[34:37], v[152:155], v[180:183], v[34:37]
	v_mfma_f32_16x16x32_bf16 v[30:33], v[152:155], v[184:187], v[30:33]
	s_waitcnt vmcnt(2)
	s_barrier
	ds_read_b128 v[66:69], v136 offset:0
	ds_read_b128 v[82:85], v137 offset:16384
	ds_read_b128 v[86:89], v137 offset:18432
	ds_read_b128 v[70:73], v136 offset:2048
	ds_read_b128 v[90:93], v137 offset:20480
	ds_read_b128 v[94:97], v137 offset:22528
	ds_read_b128 v[74:77], v136 offset:4096
	ds_read_b128 v[78:81], v136 offset:6144
	s_add_u32 m0, s64, 0xa000
	v_mfma_f32_16x16x32_bf16 v[26:29], v[156:159], v[172:175], v[26:29]
	v_mfma_f32_16x16x32_bf16 v[22:25], v[156:159], v[176:179], v[22:25]
	global_load_lds_dwordx4 v142, s[60:61]
	v_mfma_f32_16x16x32_bf16 v[18:21], v[156:159], v[180:183], v[18:21]
	v_mfma_f32_16x16x32_bf16 v[14:17], v[156:159], v[184:187], v[14:17]
	s_add_u32 m0, s64, 0xb000
	v_mfma_f32_16x16x32_bf16 v[10:13], v[168:171], v[172:175], v[10:13]
	v_mfma_f32_16x16x32_bf16 v[6:9], v[168:171], v[176:179], v[6:9]
	global_load_lds_dwordx4 v143, s[60:61]
	v_mfma_f32_16x16x32_bf16 v[2:5], v[168:171], v[180:183], v[2:5]
	v_mfma_f32_16x16x32_bf16 v[42:45], v[168:171], v[184:187], v[42:45]
	s_add_u32 s60, s60, 0x80
	s_addc_u32 s61, s61, 0
	s_mov_b32 s65, 6

.LBB0_882:
	s_mov_b64 s[14:15], 0x80
	v_lshl_add_u64 v[114:115], v[70:71], 0, s[14:15]
	v_mov_b32_e32 v38, 0
	s_mov_b32 s7, s6
	v_lshl_add_u64 v[116:117], v[114:115], 0, v[98:99]
	v_lshl_add_u64 v[118:119], v[114:115], 0, v[100:101]
	v_lshl_add_u64 v[120:121], v[114:115], 0, v[102:103]
	s_mov_b64 s[4:5], 0
	s_mov_b32 s6, 0
	v_readfirstlane_b32 s60, v104
	v_readfirstlane_b32 s61, v105
	v_readfirstlane_b32 s62, v114
	v_readfirstlane_b32 s63, v115
	v_readfirstlane_b32 s64, v122
	v_subrev_u32_e32 v140, s60, v104
	v_subrev_u32_e32 v144, s62, v114
	v_subrev_u32_e32 v145, s62, v116
	v_subrev_u32_e32 v146, s62, v118
	v_subrev_u32_e32 v147, s62, v120
	v_add_u32_e32 v141, 0x10000, v140
	v_add_u32_e32 v142, 0x20000, v140
	v_add_u32_e32 v143, 0x30000, v140
	v_add3_u32 v136, v131, v132, v133
	v_add3_u32 v137, v131, v134, v133
	v_add3_u32 v138, v130, v132, v133
	v_add3_u32 v139, v130, v134, v133
	s_add_u32 s60, s60, 0x80
	s_addc_u32 s61, s61, 0
	s_add_u32 m0, s64, 0x8000
	s_nop 0
	global_load_lds_dwordx4 v140, s[60:61]
	s_add_u32 m0, s64, 0x9000
	s_nop 0
	global_load_lds_dwordx4 v141, s[60:61]
	s_add_u32 m0, s64, 0xa000
	s_nop 0
	global_load_lds_dwordx4 v142, s[60:61]
	s_add_u32 m0, s64, 0xb000
	s_nop 0
	global_load_lds_dwordx4 v143, s[60:61]
	s_add_u32 s60, s60, 0x80
	s_addc_u32 s61, s61, 0
	s_mov_b64 s[22:23], 0x10000
	s_mov_b64 s[24:25], 0x20000
	s_mov_b64 s[26:27], 0x30000
	s_mov_b64 s[16:17], 0x10080
	s_mov_b64 s[18:19], 0x20080
	s_mov_b64 s[20:21], 0x30080
	s_waitcnt vmcnt(4) lgkmcnt(0)
	s_barrier
	ds_read_b128 v[66:69], v136 offset:0
	ds_read_b128 v[82:85], v137 offset:16384
	ds_read_b128 v[86:89], v137 offset:18432
	ds_read_b128 v[70:73], v136 offset:2048
	ds_read_b128 v[90:93], v137 offset:20480
	ds_read_b128 v[94:97], v137 offset:22528
	ds_read_b128 v[74:77], v136 offset:4096
	ds_read_b128 v[78:81], v136 offset:6144
	ds_read_b128 v[148:151], v138 offset:0
	ds_read_b128 v[172:175], v139 offset:16384
	ds_read_b128 v[176:179], v139 offset:18432
	ds_read_b128 v[152:155], v138 offset:2048
	ds_read_b128 v[180:183], v139 offset:20480
	ds_read_b128 v[184:187], v139 offset:22528
	ds_read_b128 v[156:159], v138 offset:4096
	ds_read_b128 v[168:171], v138 offset:6144
	s_waitcnt lgkmcnt(8)
	s_add_u32 m0, s64, 0xc000
	v_mfma_f32_16x16x32_bf16 v[62:65], v[66:69], v[82:85], 0
	v_mfma_f32_16x16x32_bf16 v[58:61], v[66:69], v[86:89], 0
	global_load_lds_dwordx4 v144, s[62:63]
	v_mfma_f32_16x16x32_bf16 v[54:57], v[66:69], v[90:93], 0
	v_mfma_f32_16x16x32_bf16 v[50:53], v[66:69], v[94:97], 0
	s_add_u32 m0, s64, 0xd000
	v_mfma_f32_16x16x32_bf16 v[46:49], v[70:73], v[82:85], 0
	v_mfma_f32_16x16x32_bf16 v[42:45], v[70:73], v[86:89], 0
	global_load_lds_dwordx4 v145, s[62:63]
	v_mfma_f32_16x16x32_bf16 v[34:37], v[70:73], v[90:93], 0
	v_mfma_f32_16x16x32_bf16 v[30:33], v[70:73], v[94:97], 0
	s_add_u32 m0, s64, 0xe000
	v_mfma_f32_16x16x32_bf16 v[26:29], v[74:77], v[82:85], 0
	v_mfma_f32_16x16x32_bf16 v[22:25], v[74:77], v[86:89], 0
	global_load_lds_dwordx4 v146, s[62:63]
	v_mfma_f32_16x16x32_bf16 v[18:21], v[74:77], v[90:93], 0
	v_mfma_f32_16x16x32_bf16 v[14:17], v[74:77], v[94:97], 0
	s_add_u32 m0, s64, 0xf000
	v_mfma_f32_16x16x32_bf16 v[10:13], v[78:81], v[82:85], 0
	v_mfma_f32_16x16x32_bf16 v[6:9], v[78:81], v[86:89], 0
	global_load_lds_dwordx4 v147, s[62:63]
	v_mfma_f32_16x16x32_bf16 v[2:5], v[78:81], v[90:93], 0
	v_mfma_f32_16x16x32_bf16 v[38:41], v[78:81], v[94:97], 0
	s_add_u32 s62, s62, 0x80
	s_addc_u32 s63, s63, 0
	s_waitcnt lgkmcnt(0)
	s_barrier
	s_add_u32 m0, s64, 0x0
	v_mfma_f32_16x16x32_bf16 v[62:65], v[148:151], v[172:175], v[62:65]
	v_mfma_f32_16x16x32_bf16 v[58:61], v[148:151], v[176:179], v[58:61]
	global_load_lds_dwordx4 v140, s[60:61]
	v_mfma_f32_16x16x32_bf16 v[54:57], v[148:151], v[180:183], v[54:57]
	v_mfma_f32_16x16x32_bf16 v[50:53], v[148:151], v[184:187], v[50:53]
	s_add_u32 m0, s64, 0x1000
	v_mfma_f32_16x16x32_bf16 v[46:49], v[152:155], v[172:175], v[46:49]
	v_mfma_f32_16x16x32_bf16 v[42:45], v[152:155], v[176:179], v[42:45]
	global_load_lds_dwordx4 v141, s[60:61]
	v_mfma_f32_16x16x32_bf16 v[34:37], v[152:155], v[180:183], v[34:37]
	v_mfma_f32_16x16x32_bf16 v[30:33], v[152:155], v[184:187], v[30:33]
	s_waitcnt vmcnt(2)
	s_barrier
	ds_read_b128 v[66:69], v136 offset:32768
	ds_read_b128 v[82:85], v137 offset:49152
	ds_read_b128 v[86:89], v137 offset:51200
	ds_read_b128 v[70:73], v136 offset:34816
	ds_read_b128 v[90:93], v137 offset:53248
	ds_read_b128 v[94:97], v137 offset:55296
	ds_read_b128 v[74:77], v136 offset:36864
	ds_read_b128 v[78:81], v136 offset:38912
	s_add_u32 m0, s64, 0x2000
	v_mfma_f32_16x16x32_bf16 v[26:29], v[156:159], v[172:175], v[26:29]
	v_mfma_f32_16x16x32_bf16 v[22:25], v[156:159], v[176:179], v[22:25]
	global_load_lds_dwordx4 v142, s[60:61]
	v_mfma_f32_16x16x32_bf16 v[18:21], v[156:159], v[180:183], v[18:21]
	v_mfma_f32_16x16x32_bf16 v[14:17], v[156:159], v[184:187], v[14:17]
	s_add_u32 m0, s64, 0x3000
	v_mfma_f32_16x16x32_bf16 v[10:13], v[168:171], v[172:175], v[10:13]
	v_mfma_f32_16x16x32_bf16 v[6:9], v[168:171], v[176:179], v[6:9]
	global_load_lds_dwordx4 v143, s[60:61]
	v_mfma_f32_16x16x32_bf16 v[2:5], v[168:171], v[180:183], v[2:5]
	v_mfma_f32_16x16x32_bf16 v[38:41], v[168:171], v[184:187], v[38:41]
	s_add_u32 s60, s60, 0x80
	s_addc_u32 s61, s61, 0
	ds_read_b128 v[148:151], v138 offset:32768
	ds_read_b128 v[172:175], v139 offset:49152
	ds_read_b128 v[176:179], v139 offset:51200
	ds_read_b128 v[152:155], v138 offset:34816
	ds_read_b128 v[180:183], v139 offset:53248
	ds_read_b128 v[184:187], v139 offset:55296
	ds_read_b128 v[156:159], v138 offset:36864
	ds_read_b128 v[168:171], v138 offset:38912
	s_waitcnt lgkmcnt(8)
	s_add_u32 m0, s64, 0x4000
	v_mfma_f32_16x16x32_bf16 v[62:65], v[66:69], v[82:85], v[62:65]
	v_mfma_f32_16x16x32_bf16 v[58:61], v[66:69], v[86:89], v[58:61]
	global_load_lds_dwordx4 v144, s[62:63]
	v_mfma_f32_16x16x32_bf16 v[54:57], v[66:69], v[90:93], v[54:57]
	v_mfma_f32_16x16x32_bf16 v[50:53], v[66:69], v[94:97], v[50:53]
	s_add_u32 m0, s64, 0x5000
	v_mfma_f32_16x16x32_bf16 v[46:49], v[70:73], v[82:85], v[46:49]
	v_mfma_f32_16x16x32_bf16 v[42:45], v[70:73], v[86:89], v[42:45]
	global_load_lds_dwordx4 v145, s[62:63]
	v_mfma_f32_16x16x32_bf16 v[34:37], v[70:73], v[90:93], v[34:37]
	v_mfma_f32_16x16x32_bf16 v[30:33], v[70:73], v[94:97], v[30:33]
	s_add_u32 m0, s64, 0x6000
	v_mfma_f32_16x16x32_bf16 v[26:29], v[74:77], v[82:85], v[26:29]
	v_mfma_f32_16x16x32_bf16 v[22:25], v[74:77], v[86:89], v[22:25]
	global_load_lds_dwordx4 v146, s[62:63]
	v_mfma_f32_16x16x32_bf16 v[18:21], v[74:77], v[90:93], v[18:21]
	v_mfma_f32_16x16x32_bf16 v[14:17], v[74:77], v[94:97], v[14:17]
	s_add_u32 m0, s64, 0x7000
	v_mfma_f32_16x16x32_bf16 v[10:13], v[78:81], v[82:85], v[10:13]
	v_mfma_f32_16x16x32_bf16 v[6:9], v[78:81], v[86:89], v[6:9]
	global_load_lds_dwordx4 v147, s[62:63]
	v_mfma_f32_16x16x32_bf16 v[2:5], v[78:81], v[90:93], v[2:5]
	v_mfma_f32_16x16x32_bf16 v[38:41], v[78:81], v[94:97], v[38:41]
	s_add_u32 s62, s62, 0x80
	s_addc_u32 s63, s63, 0
	s_waitcnt lgkmcnt(0)
	s_barrier
	s_add_u32 m0, s64, 0x8000
	v_mfma_f32_16x16x32_bf16 v[62:65], v[148:151], v[172:175], v[62:65]
	v_mfma_f32_16x16x32_bf16 v[58:61], v[148:151], v[176:179], v[58:61]
	global_load_lds_dwordx4 v140, s[60:61]
	v_mfma_f32_16x16x32_bf16 v[54:57], v[148:151], v[180:183], v[54:57]
	v_mfma_f32_16x16x32_bf16 v[50:53], v[148:151], v[184:187], v[50:53]
	s_add_u32 m0, s64, 0x9000
	v_mfma_f32_16x16x32_bf16 v[46:49], v[152:155], v[172:175], v[46:49]
	v_mfma_f32_16x16x32_bf16 v[42:45], v[152:155], v[176:179], v[42:45]
	global_load_lds_dwordx4 v141, s[60:61]
	v_mfma_f32_16x16x32_bf16 v[34:37], v[152:155], v[180:183], v[34:37]
	v_mfma_f32_16x16x32_bf16 v[30:33], v[152:155], v[184:187], v[30:33]
	s_waitcnt vmcnt(2)
	s_barrier
	ds_read_b128 v[66:69], v136 offset:0
	ds_read_b128 v[82:85], v137 offset:16384
	ds_read_b128 v[86:89], v137 offset:18432
	ds_read_b128 v[70:73], v136 offset:2048
	ds_read_b128 v[90:93], v137 offset:20480
	ds_read_b128 v[94:97], v137 offset:22528
	ds_read_b128 v[74:77], v136 offset:4096
	ds_read_b128 v[78:81], v136 offset:6144
	s_add_u32 m0, s64, 0xa000
	v_mfma_f32_16x16x32_bf16 v[26:29], v[156:159], v[172:175], v[26:29]
	v_mfma_f32_16x16x32_bf16 v[22:25], v[156:159], v[176:179], v[22:25]
	global_load_lds_dwordx4 v142, s[60:61]
	v_mfma_f32_16x16x32_bf16 v[18:21], v[156:159], v[180:183], v[18:21]
	v_mfma_f32_16x16x32_bf16 v[14:17], v[156:159], v[184:187], v[14:17]
	s_add_u32 m0, s64, 0xb000
	v_mfma_f32_16x16x32_bf16 v[10:13], v[168:171], v[172:175], v[10:13]
	v_mfma_f32_16x16x32_bf16 v[6:9], v[168:171], v[176:179], v[6:9]
	global_load_lds_dwordx4 v143, s[60:61]
	v_mfma_f32_16x16x32_bf16 v[2:5], v[168:171], v[180:183], v[2:5]
	v_mfma_f32_16x16x32_bf16 v[38:41], v[168:171], v[184:187], v[38:41]
	s_add_u32 s60, s60, 0x80
	s_addc_u32 s61, s61, 0
	s_mov_b32 s65, 6
